# E11: SwiGLU epilogue row-statistics loads issued before the align barrier (loads only), on N5 base
# baseline (speedup 1.0000x reference)
.LBB0_304:
	ds_read_b128 v[142:145], v136
	ds_read_b128 v[170:173], v136 offset:1024
	ds_read_b128 v[174:177], v136 offset:2048
	ds_read_b128 v[178:181], v136 offset:3072
	ds_read_b128 v[182:185], v137
	ds_read_b128 v[186:189], v137 offset:1024
	ds_read_b128 v[190:193], v137 offset:2048
	ds_read_b128 v[194:197], v137 offset:3072
	s_add_i32 s42, s94, 0xfff80080
	s_cmp_eq_u32 vcc_lo, 28
	s_cselect_b32 s97, s8, s42
	s_cselect_b32 s52, s9, s95
	s_or_b32 vcc_hi, s97, 0x80
	s_mov_b32 m0, s72
	ds_read_b128 v[198:201], v138
	ds_read_b128 v[202:205], v138 offset:1024
	ds_read_b128 v[228:231], v138 offset:2048
	ds_read_b128 v[232:235], v138 offset:3072
	ds_read_b128 v[236:239], v138 offset:4096
	ds_read_b128 v[240:243], v138 offset:5120
	ds_read_b128 v[244:247], v138 offset:6144
	ds_read_b128 v[248:251], v138 offset:7168
	buffer_load_dwordx4 v132, s[60:63], s94 offen lds
	s_mov_b32 m0, s47
	s_nop 0
	buffer_load_dwordx4 v134, s[60:63], s94 offen lds
	s_waitcnt vmcnt(8)
	s_waitcnt lgkmcnt(0)
	s_setprio 1
	s_barrier
	v_mfma_f32_16x16x32_bf16 v[114:117], v[142:145], v[198:201], v[114:117]
	v_mfma_f32_16x16x32_bf16 v[110:113], v[174:177], v[198:201], v[110:113]
	v_mfma_f32_16x16x32_bf16 v[106:109], v[142:145], v[228:231], v[106:109]
	v_mfma_f32_16x16x32_bf16 v[102:105], v[174:177], v[228:231], v[102:105]
	v_mfma_f32_16x16x32_bf16 v[94:97], v[142:145], v[236:239], v[94:97]
	v_mfma_f32_16x16x32_bf16 v[86:89], v[174:177], v[236:239], v[86:89]
	v_mfma_f32_16x16x32_bf16 v[78:81], v[142:145], v[244:247], v[78:81]
	v_mfma_f32_16x16x32_bf16 v[70:73], v[174:177], v[244:247], v[70:73]
	v_mfma_f32_16x16x32_bf16 v[114:117], v[170:173], v[202:205], v[114:117]
	v_mfma_f32_16x16x32_bf16 v[110:113], v[178:181], v[202:205], v[110:113]
	v_mfma_f32_16x16x32_bf16 v[106:109], v[170:173], v[232:235], v[106:109]
	v_mfma_f32_16x16x32_bf16 v[102:105], v[178:181], v[232:235], v[102:105]
	v_mfma_f32_16x16x32_bf16 v[94:97], v[170:173], v[240:243], v[94:97]
	v_mfma_f32_16x16x32_bf16 v[86:89], v[178:181], v[240:243], v[86:89]
	v_mfma_f32_16x16x32_bf16 v[78:81], v[170:173], v[248:251], v[78:81]
	v_mfma_f32_16x16x32_bf16 v[70:73], v[178:181], v[248:251], v[70:73]
	v_mfma_f32_16x16x32_bf16 v[126:129], v[182:185], v[198:201], v[126:129]
	v_mfma_f32_16x16x32_bf16 v[122:125], v[190:193], v[198:201], v[122:125]
	v_mfma_f32_16x16x32_bf16 v[118:121], v[182:185], v[228:231], v[118:121]
	v_mfma_f32_16x16x32_bf16 v[98:101], v[190:193], v[228:231], v[98:101]
	v_mfma_f32_16x16x32_bf16 v[90:93], v[182:185], v[236:239], v[90:93]
	v_mfma_f32_16x16x32_bf16 v[82:85], v[190:193], v[236:239], v[82:85]
	v_mfma_f32_16x16x32_bf16 v[74:77], v[182:185], v[244:247], v[74:77]
	v_mfma_f32_16x16x32_bf16 v[66:69], v[190:193], v[244:247], v[66:69]
	v_mfma_f32_16x16x32_bf16 v[126:129], v[186:189], v[202:205], v[126:129]
	v_mfma_f32_16x16x32_bf16 v[122:125], v[194:197], v[202:205], v[122:125]
	v_mfma_f32_16x16x32_bf16 v[118:121], v[186:189], v[232:235], v[118:121]
	v_mfma_f32_16x16x32_bf16 v[98:101], v[194:197], v[232:235], v[98:101]
	v_mfma_f32_16x16x32_bf16 v[90:93], v[186:189], v[240:243], v[90:93]
	v_mfma_f32_16x16x32_bf16 v[82:85], v[194:197], v[240:243], v[82:85]
	v_mfma_f32_16x16x32_bf16 v[74:77], v[186:189], v[248:251], v[74:77]
	v_mfma_f32_16x16x32_bf16 v[66:69], v[194:197], v[248:251], v[66:69]
	s_barrier
	s_setprio 0
	s_mov_b32 m0, s13
	s_mov_b32 s42, s62
	s_mov_b32 s43, s63
	ds_read_b128 v[198:201], v138 offset:16384
	ds_read_b128 v[202:205], v138 offset:17408
	ds_read_b128 v[228:231], v138 offset:18432
	ds_read_b128 v[232:235], v138 offset:19456
	ds_read_b128 v[236:239], v138 offset:20480
	ds_read_b128 v[240:243], v138 offset:21504
	ds_read_b128 v[244:247], v138 offset:22528
	ds_read_b128 v[248:251], v138 offset:23552
	buffer_load_dwordx4 v133, s[40:43], s52 offen lds
	s_mov_b32 m0, s14
	s_add_i32 s96, s52, 0x80000
	buffer_load_dwordx4 v135, s[40:43], s52 offen lds
	s_mov_b32 m0, s15
	s_nop 0
	buffer_load_dwordx4 v133, s[40:43], s96 offen lds
	s_mov_b32 m0, s16
	s_nop 0
	buffer_load_dwordx4 v135, s[40:43], s96 offen lds
	s_mov_b32 m0, s2
	s_nop 0
	buffer_load_dwordx4 v132, s[60:63], s97 offen lds
	s_mov_b32 m0, s21
	s_nop 0
	buffer_load_dwordx4 v134, s[60:63], s97 offen lds
	s_waitcnt vmcnt(8)
	s_waitcnt lgkmcnt(0)
	s_setprio 1
	s_barrier
	v_mfma_f32_16x16x32_bf16 v[62:65], v[142:145], v[198:201], v[62:65]
	v_mfma_f32_16x16x32_bf16 v[54:57], v[174:177], v[198:201], v[54:57]
	v_mfma_f32_16x16x32_bf16 v[46:49], v[142:145], v[228:231], v[46:49]
	v_mfma_f32_16x16x32_bf16 v[38:41], v[174:177], v[228:231], v[38:41]
	v_mfma_f32_16x16x32_bf16 v[30:33], v[142:145], v[236:239], v[30:33]
	v_mfma_f32_16x16x32_bf16 v[22:25], v[174:177], v[236:239], v[22:25]
	v_mfma_f32_16x16x32_bf16 v[14:17], v[142:145], v[244:247], v[14:17]
	v_mfma_f32_16x16x32_bf16 v[6:9], v[174:177], v[244:247], v[6:9]
	v_mfma_f32_16x16x32_bf16 v[62:65], v[170:173], v[202:205], v[62:65]
	v_mfma_f32_16x16x32_bf16 v[54:57], v[178:181], v[202:205], v[54:57]
	v_mfma_f32_16x16x32_bf16 v[46:49], v[170:173], v[232:235], v[46:49]
	v_mfma_f32_16x16x32_bf16 v[38:41], v[178:181], v[232:235], v[38:41]
	v_mfma_f32_16x16x32_bf16 v[30:33], v[170:173], v[240:243], v[30:33]
	v_mfma_f32_16x16x32_bf16 v[22:25], v[178:181], v[240:243], v[22:25]
	v_mfma_f32_16x16x32_bf16 v[14:17], v[170:173], v[248:251], v[14:17]
	v_mfma_f32_16x16x32_bf16 v[6:9], v[178:181], v[248:251], v[6:9]
	v_mfma_f32_16x16x32_bf16 v[58:61], v[182:185], v[198:201], v[58:61]
	v_mfma_f32_16x16x32_bf16 v[50:53], v[190:193], v[198:201], v[50:53]
	v_mfma_f32_16x16x32_bf16 v[42:45], v[182:185], v[228:231], v[42:45]
	v_mfma_f32_16x16x32_bf16 v[34:37], v[190:193], v[228:231], v[34:37]
	v_mfma_f32_16x16x32_bf16 v[26:29], v[182:185], v[236:239], v[26:29]
	v_mfma_f32_16x16x32_bf16 v[18:21], v[190:193], v[236:239], v[18:21]
	v_mfma_f32_16x16x32_bf16 v[10:13], v[182:185], v[244:247], v[10:13]
	v_mfma_f32_16x16x32_bf16 v[2:5], v[190:193], v[244:247], v[2:5]
	v_mfma_f32_16x16x32_bf16 v[58:61], v[186:189], v[202:205], v[58:61]
	v_mfma_f32_16x16x32_bf16 v[50:53], v[194:197], v[202:205], v[50:53]
	v_mfma_f32_16x16x32_bf16 v[42:45], v[186:189], v[232:235], v[42:45]
	v_mfma_f32_16x16x32_bf16 v[34:37], v[194:197], v[232:235], v[34:37]
	v_mfma_f32_16x16x32_bf16 v[26:29], v[186:189], v[240:243], v[26:29]
	v_mfma_f32_16x16x32_bf16 v[18:21], v[194:197], v[240:243], v[18:21]
	v_mfma_f32_16x16x32_bf16 v[10:13], v[186:189], v[248:251], v[10:13]
	v_mfma_f32_16x16x32_bf16 v[2:5], v[194:197], v[248:251], v[2:5]
	s_barrier
	s_setprio 0
	ds_read_b128 v[142:145], v139
	ds_read_b128 v[170:173], v139 offset:1024
	ds_read_b128 v[174:177], v139 offset:2048
	ds_read_b128 v[178:181], v139 offset:3072
	ds_read_b128 v[182:185], v140
	ds_read_b128 v[186:189], v140 offset:1024
	ds_read_b128 v[190:193], v140 offset:2048
	ds_read_b128 v[194:197], v140 offset:3072
	s_add_i32 s97, s97, 0x80000
	s_mov_b32 m0, s23
	ds_read_b128 v[198:201], v138 offset:32768
	ds_read_b128 v[202:205], v138 offset:33792
	ds_read_b128 v[228:231], v138 offset:34816
	ds_read_b128 v[232:235], v138 offset:35840
	ds_read_b128 v[236:239], v138 offset:36864
	ds_read_b128 v[240:243], v138 offset:37888
	ds_read_b128 v[244:247], v138 offset:38912
	ds_read_b128 v[248:251], v138 offset:39936
	buffer_load_dwordx4 v132, s[60:63], s97 offen lds
	s_mov_b32 m0, s24
	s_nop 0
	buffer_load_dwordx4 v134, s[60:63], s97 offen lds
	s_waitcnt vmcnt(8)
	s_waitcnt lgkmcnt(0)
	s_setprio 1
	s_barrier
	v_mfma_f32_16x16x32_bf16 v[114:117], v[142:145], v[198:201], v[114:117]
	v_mfma_f32_16x16x32_bf16 v[110:113], v[174:177], v[198:201], v[110:113]
	v_mfma_f32_16x16x32_bf16 v[106:109], v[142:145], v[228:231], v[106:109]
	v_mfma_f32_16x16x32_bf16 v[102:105], v[174:177], v[228:231], v[102:105]
	v_mfma_f32_16x16x32_bf16 v[94:97], v[142:145], v[236:239], v[94:97]
	v_mfma_f32_16x16x32_bf16 v[86:89], v[174:177], v[236:239], v[86:89]
	v_mfma_f32_16x16x32_bf16 v[78:81], v[142:145], v[244:247], v[78:81]
	v_mfma_f32_16x16x32_bf16 v[70:73], v[174:177], v[244:247], v[70:73]
	v_mfma_f32_16x16x32_bf16 v[114:117], v[170:173], v[202:205], v[114:117]
	v_mfma_f32_16x16x32_bf16 v[110:113], v[178:181], v[202:205], v[110:113]
	v_mfma_f32_16x16x32_bf16 v[106:109], v[170:173], v[232:235], v[106:109]
	v_mfma_f32_16x16x32_bf16 v[102:105], v[178:181], v[232:235], v[102:105]
	v_mfma_f32_16x16x32_bf16 v[94:97], v[170:173], v[240:243], v[94:97]
	v_mfma_f32_16x16x32_bf16 v[86:89], v[178:181], v[240:243], v[86:89]
	v_mfma_f32_16x16x32_bf16 v[78:81], v[170:173], v[248:251], v[78:81]
	v_mfma_f32_16x16x32_bf16 v[70:73], v[178:181], v[248:251], v[70:73]
	v_mfma_f32_16x16x32_bf16 v[126:129], v[182:185], v[198:201], v[126:129]
	v_mfma_f32_16x16x32_bf16 v[122:125], v[190:193], v[198:201], v[122:125]
	v_mfma_f32_16x16x32_bf16 v[118:121], v[182:185], v[228:231], v[118:121]
	v_mfma_f32_16x16x32_bf16 v[98:101], v[190:193], v[228:231], v[98:101]
	v_mfma_f32_16x16x32_bf16 v[90:93], v[182:185], v[236:239], v[90:93]
	v_mfma_f32_16x16x32_bf16 v[82:85], v[190:193], v[236:239], v[82:85]
	v_mfma_f32_16x16x32_bf16 v[74:77], v[182:185], v[244:247], v[74:77]
	v_mfma_f32_16x16x32_bf16 v[66:69], v[190:193], v[244:247], v[66:69]
	v_mfma_f32_16x16x32_bf16 v[126:129], v[186:189], v[202:205], v[126:129]
	v_mfma_f32_16x16x32_bf16 v[122:125], v[194:197], v[202:205], v[122:125]
	v_mfma_f32_16x16x32_bf16 v[118:121], v[186:189], v[232:235], v[118:121]
	v_mfma_f32_16x16x32_bf16 v[98:101], v[194:197], v[232:235], v[98:101]
	v_mfma_f32_16x16x32_bf16 v[90:93], v[186:189], v[240:243], v[90:93]
	v_mfma_f32_16x16x32_bf16 v[82:85], v[194:197], v[240:243], v[82:85]
	v_mfma_f32_16x16x32_bf16 v[74:77], v[186:189], v[248:251], v[74:77]
	v_mfma_f32_16x16x32_bf16 v[66:69], v[194:197], v[248:251], v[66:69]
	s_barrier
	s_setprio 0
	s_mov_b32 m0, s31
	s_or_b32 s53, s52, 0x80
	ds_read_b128 v[198:201], v138 offset:49152
	ds_read_b128 v[202:205], v138 offset:50176
	ds_read_b128 v[228:231], v138 offset:51200
	ds_read_b128 v[232:235], v138 offset:52224
	ds_read_b128 v[236:239], v138 offset:53248
	ds_read_b128 v[240:243], v138 offset:54272
	ds_read_b128 v[244:247], v138 offset:55296
	ds_read_b128 v[248:251], v138 offset:56320
	buffer_load_dwordx4 v133, s[40:43], s53 offen lds
	s_mov_b32 m0, s33
	s_add_i32 s52, s52, 0x80080
	buffer_load_dwordx4 v135, s[40:43], s53 offen lds
	s_mov_b32 m0, s68
	s_nop 0
	buffer_load_dwordx4 v133, s[40:43], s52 offen lds
	s_mov_b32 m0, s69
	s_nop 0
	buffer_load_dwordx4 v135, s[40:43], s52 offen lds
	s_mov_b32 m0, s36
	s_nop 0
	buffer_load_dwordx4 v132, s[60:63], vcc_hi offen lds
	s_mov_b32 m0, s37
	s_nop 0
	buffer_load_dwordx4 v134, s[60:63], vcc_hi offen lds
	s_waitcnt vmcnt(8)
	s_waitcnt lgkmcnt(0)
	s_setprio 1
	s_barrier
	v_mfma_f32_16x16x32_bf16 v[62:65], v[142:145], v[198:201], v[62:65]
	v_mfma_f32_16x16x32_bf16 v[54:57], v[174:177], v[198:201], v[54:57]
	v_mfma_f32_16x16x32_bf16 v[46:49], v[142:145], v[228:231], v[46:49]
	v_mfma_f32_16x16x32_bf16 v[38:41], v[174:177], v[228:231], v[38:41]
	v_mfma_f32_16x16x32_bf16 v[30:33], v[142:145], v[236:239], v[30:33]
	v_mfma_f32_16x16x32_bf16 v[22:25], v[174:177], v[236:239], v[22:25]
	v_mfma_f32_16x16x32_bf16 v[14:17], v[142:145], v[244:247], v[14:17]
	v_mfma_f32_16x16x32_bf16 v[6:9], v[174:177], v[244:247], v[6:9]
	v_mfma_f32_16x16x32_bf16 v[62:65], v[170:173], v[202:205], v[62:65]
	v_mfma_f32_16x16x32_bf16 v[54:57], v[178:181], v[202:205], v[54:57]
	v_mfma_f32_16x16x32_bf16 v[46:49], v[170:173], v[232:235], v[46:49]
	v_mfma_f32_16x16x32_bf16 v[38:41], v[178:181], v[232:235], v[38:41]
	v_mfma_f32_16x16x32_bf16 v[30:33], v[170:173], v[240:243], v[30:33]
	v_mfma_f32_16x16x32_bf16 v[22:25], v[178:181], v[240:243], v[22:25]
	v_mfma_f32_16x16x32_bf16 v[14:17], v[170:173], v[248:251], v[14:17]
	v_mfma_f32_16x16x32_bf16 v[6:9], v[178:181], v[248:251], v[6:9]
	v_mfma_f32_16x16x32_bf16 v[58:61], v[182:185], v[198:201], v[58:61]
	v_mfma_f32_16x16x32_bf16 v[50:53], v[190:193], v[198:201], v[50:53]
	v_mfma_f32_16x16x32_bf16 v[42:45], v[182:185], v[228:231], v[42:45]
	v_mfma_f32_16x16x32_bf16 v[34:37], v[190:193], v[228:231], v[34:37]
	v_mfma_f32_16x16x32_bf16 v[26:29], v[182:185], v[236:239], v[26:29]
	v_mfma_f32_16x16x32_bf16 v[18:21], v[190:193], v[236:239], v[18:21]
	v_mfma_f32_16x16x32_bf16 v[10:13], v[182:185], v[244:247], v[10:13]
	v_mfma_f32_16x16x32_bf16 v[2:5], v[190:193], v[244:247], v[2:5]
	v_mfma_f32_16x16x32_bf16 v[58:61], v[186:189], v[202:205], v[58:61]
	v_mfma_f32_16x16x32_bf16 v[50:53], v[194:197], v[202:205], v[50:53]
	v_mfma_f32_16x16x32_bf16 v[42:45], v[186:189], v[232:235], v[42:45]
	v_mfma_f32_16x16x32_bf16 v[34:37], v[194:197], v[232:235], v[34:37]
	v_mfma_f32_16x16x32_bf16 v[26:29], v[186:189], v[240:243], v[26:29]
	v_mfma_f32_16x16x32_bf16 v[18:21], v[194:197], v[240:243], v[18:21]
	v_mfma_f32_16x16x32_bf16 v[10:13], v[186:189], v[248:251], v[10:13]
	v_mfma_f32_16x16x32_bf16 v[2:5], v[194:197], v[248:251], v[2:5]
	s_barrier
	s_setprio 0
	s_add_i32 vcc_lo, vcc_lo, 2
	s_addk_i32 s94, 0x100
	s_addk_i32 s95, 0x100
	s_cmp_gt_u32 vcc_lo, 29
	s_cbranch_scc0 .LBB0_304
	s_lshl_b32 s8, s93, 8
	s_add_i32 s8, s8, s46
	s_ashr_i32 s9, s8, 31
	v_lshl_add_u64 v[142:143], s[8:9], 3, v[130:131]
	global_load_dwordx2 v[144:145], v[142:143], off
	global_load_dwordx2 v[154:155], v[142:143], off offset:128
	global_load_dwordx2 v[178:179], v[142:143], off offset:256
	global_load_dwordx2 v[182:183], v[142:143], off offset:384
	global_load_dwordx2 v[184:185], v[142:143], off offset:1024
	global_load_dwordx2 v[186:187], v[142:143], off offset:1152
	global_load_dwordx2 v[188:189], v[142:143], off offset:1280
	global_load_dwordx2 v[190:191], v[142:143], off offset:1408
	s_and_b64 vcc, exec, s[48:49]
	s_cbranch_vccz .LBB0_307
	s_barrier
.LBB0_307:
	v_pk_mul_f32 v[156:157], v[114:115], v[126:127]
	v_pk_mul_f32 v[170:171], v[112:113], v[124:125]
	v_pk_mul_f32 v[172:173], v[110:111], v[122:123]
	v_pk_mul_f32 v[174:175], v[108:109], v[120:121]
	v_pk_mul_f32 v[176:177], v[106:107], v[118:119]
	s_flbit_i32_b32 s8, 0
	s_min_u32 s42, s8, 32
	s_mul_i32 s8, s93, 0x58
	s_sub_i32 s93, 32, s42
	v_pk_mul_f32 v[128:129], v[116:117], v[128:129]
	s_lshl_b32 s9, s92, 1
	s_or_b32 s9, s9, s73
	s_add_i32 s8, s9, s8
	s_ashr_i32 s9, s8, 31
	s_lshl_b64 s[8:9], s[8:9], 15
	s_add_u32 s43, s25, s8
	s_addc_u32 s92, s30, s9
	s_add_u32 s8, s43, s64
	s_addc_u32 s9, s92, s65
	s_add_u32 s8, s8, s88
	s_addc_u32 s9, s9, 0
	v_pk_mul_f32 v[98:99], v[102:103], v[98:99]
	v_pk_mul_f32 v[100:101], v[104:105], v[100:101]
	v_pk_mul_f32 v[90:91], v[94:95], v[90:91]
	v_pk_mul_f32 v[92:93], v[96:97], v[92:93]
	v_pk_mul_f32 v[82:83], v[86:87], v[82:83]
	v_pk_mul_f32 v[84:85], v[88:89], v[84:85]
	v_pk_mul_f32 v[74:75], v[78:79], v[74:75]
	v_pk_mul_f32 v[76:77], v[80:81], v[76:77]
	v_pk_mul_f32 v[66:67], v[70:71], v[66:67]
	v_pk_mul_f32 v[68:69], v[72:73], v[68:69]
	v_pk_mul_f32 v[58:59], v[62:63], v[58:59]
	v_pk_mul_f32 v[60:61], v[64:65], v[60:61]
	v_pk_mul_f32 v[50:51], v[54:55], v[50:51]
	v_pk_mul_f32 v[52:53], v[56:57], v[52:53]
	v_pk_mul_f32 v[42:43], v[46:47], v[42:43]
	v_pk_mul_f32 v[44:45], v[48:49], v[44:45]
	v_pk_mul_f32 v[34:35], v[38:39], v[34:35]
	v_pk_mul_f32 v[36:37], v[40:41], v[36:37]
	v_pk_mul_f32 v[26:27], v[30:31], v[26:27]
	v_pk_mul_f32 v[28:29], v[32:33], v[28:29]
	v_pk_mul_f32 v[18:19], v[22:23], v[18:19]
	v_pk_mul_f32 v[20:21], v[24:25], v[20:21]
	v_pk_mul_f32 v[12:13], v[16:17], v[12:13]
	v_pk_mul_f32 v[10:11], v[14:15], v[10:11]
	v_pk_mul_f32 v[4:5], v[8:9], v[4:5]
	v_pk_mul_f32 v[2:3], v[6:7], v[2:3]
	v_readlane_b32 s97, v252, 18
	v_readlane_b32 s96, v252, 46
	s_waitcnt vmcnt(0)
	v_mov_b32_e32 v146, v145
	v_lshlrev_b64 v[142:143], s42, v[146:147]
	v_min_u32_e32 v142, 1, v142
	s_waitcnt vmcnt(6)
	v_mov_b32_e32 v146, v155
	v_or_b32_e32 v143, v143, v142
	v_cvt_f32_u32_e32 v180, v144
	v_lshlrev_b64 v[144:145], s42, v[146:147]
	v_cvt_f32_u32_e32 v143, v143
	v_min_u32_e32 v146, 1, v144
	v_or_b32_e32 v145, v145, v146
	v_cvt_f32_u32_e32 v154, v154
	v_cvt_f32_u32_e32 v145, v145
	v_fmamk_f32 v142, v180, 0x30000000, v209
	v_ldexp_f32 v143, v143, s93
	v_fmac_f32_e32 v142, 2.0, v143
	v_rsq_f32_e32 v143, v142
	v_fmamk_f32 v144, v154, 0x30000000, v209
	v_ldexp_f32 v145, v145, s93
	v_fmac_f32_e32 v144, 2.0, v145
	v_rsq_f32_e32 v145, v144
	v_mul_f32_e32 v146, 0xbfb8aa3b, v143
	v_pk_mul_f32 v[114:115], v[114:115], v[146:147] op_sel_hi:[1,0]
	v_pk_mul_f32 v[116:117], v[116:117], v[146:147] op_sel_hi:[1,0]
	v_exp_f32_e32 v114, v114
	v_exp_f32_e32 v115, v115
	v_pk_mul_f32 v[110:111], v[110:111], v[146:147] op_sel_hi:[1,0]
	v_pk_mul_f32 v[112:113], v[112:113], v[146:147] op_sel_hi:[1,0]
	v_mul_f32_e32 v146, 0xbfb8aa3b, v145
	v_exp_f32_e32 v116, v116
	v_exp_f32_e32 v117, v117
	v_exp_f32_e32 v110, v110
	v_exp_f32_e32 v111, v111
	v_exp_f32_e32 v112, v112
	v_exp_f32_e32 v113, v113
	v_pk_mul_f32 v[154:155], v[102:103], v[146:147] op_sel_hi:[1,0]
	v_pk_mul_f32 v[106:107], v[106:107], v[146:147] op_sel_hi:[1,0]
	v_exp_f32_e32 v154, v154
	v_exp_f32_e32 v155, v155
	v_pk_mul_f32 v[108:109], v[108:109], v[146:147] op_sel_hi:[1,0]
	v_exp_f32_e32 v106, v106
	v_exp_f32_e32 v107, v107
	v_pk_fma_f32 v[114:115], v[142:143], v[114:115], v[142:143] op_sel_hi:[0,1,0]
	v_pk_mul_f32 v[180:181], v[104:105], v[146:147] op_sel_hi:[1,0]
	v_exp_f32_e32 v108, v108
	v_exp_f32_e32 v109, v109
	v_pk_fma_f32 v[116:117], v[142:143], v[116:117], v[142:143] op_sel_hi:[0,1,0]
	v_rcp_f32_e32 v114, v114
	v_rcp_f32_e32 v115, v115
	v_exp_f32_e32 v180, v180
	v_exp_f32_e32 v181, v181
	v_pk_fma_f32 v[110:111], v[142:143], v[110:111], v[142:143] op_sel_hi:[0,1,0]
	v_pk_fma_f32 v[112:113], v[142:143], v[112:113], v[142:143] op_sel_hi:[0,1,0]
	v_rcp_f32_e32 v116, v116
	v_rcp_f32_e32 v117, v117
	v_rcp_f32_e32 v110, v110
	v_rcp_f32_e32 v111, v111
	v_rcp_f32_e32 v112, v112
	v_rcp_f32_e32 v113, v113
	v_pk_fma_f32 v[142:143], v[144:145], v[154:155], v[144:145] op_sel_hi:[0,1,0]
	v_pk_fma_f32 v[106:107], v[144:145], v[106:107], v[144:145] op_sel_hi:[0,1,0]
	v_rcp_f32_e32 v142, v142
	v_rcp_f32_e32 v143, v143
	v_pk_fma_f32 v[108:109], v[144:145], v[108:109], v[144:145] op_sel_hi:[0,1,0]
	v_rcp_f32_e32 v154, v106
	v_rcp_f32_e32 v155, v107
	v_pk_mul_f32 v[106:107], v[156:157], v[114:115]
	v_pk_fma_f32 v[144:145], v[144:145], v[180:181], v[144:145] op_sel_hi:[0,1,0]
	v_rcp_f32_e32 v180, v108
	v_rcp_f32_e32 v181, v109
	v_pk_mul_f32 v[108:109], v[128:129], v[116:117]
	v_cvt_pk_bf16_f32 v106, v106, v107
	v_pk_mul_f32 v[110:111], v[172:173], v[110:111]
	v_cvt_pk_bf16_f32 v107, v108, v109
	v_pk_mul_f32 v[112:113], v[170:171], v[112:113]
	v_cvt_pk_bf16_f32 v108, v110, v111
	s_waitcnt vmcnt(5)
	v_mov_b32_e32 v146, v179
	v_cvt_pk_bf16_f32 v109, v112, v113
	global_store_dwordx4 v141, v[106:109], s[8:9]
	v_pk_mul_f32 v[102:103], v[98:99], v[142:143]
	v_lshlrev_b64 v[98:99], s42, v[146:147]
	v_rcp_f32_e32 v106, v144
	v_rcp_f32_e32 v107, v145
	v_min_u32_e32 v98, 1, v98
	v_or_b32_e32 v98, v99, v98
	s_add_u32 s8, s43, s66
	v_pk_mul_f32 v[104:105], v[100:101], v[106:107]
	v_cvt_f32_u32_e32 v100, v178
	v_cvt_f32_u32_e32 v101, v98
	s_addc_u32 s9, s92, s67
	s_add_u32 s8, s8, s88
	v_fmamk_f32 v106, v100, 0x30000000, v209
	v_ldexp_f32 v100, v101, s93
	v_fmac_f32_e32 v106, 2.0, v100
	v_rsq_f32_e32 v107, v106
	v_pk_mul_f32 v[110:111], v[176:177], v[154:155]
	s_addc_u32 s9, s9, 0
	v_cvt_pk_bf16_f32 v98, v110, v111
	v_pk_mul_f32 v[112:113], v[174:175], v[180:181]
	s_waitcnt vmcnt(5)
	v_mov_b32_e32 v146, v183
	v_cvt_pk_bf16_f32 v99, v112, v113
	v_cvt_pk_bf16_f32 v100, v102, v103
	v_cvt_pk_bf16_f32 v101, v104, v105
	global_store_dwordx4 v141, v[98:101], s[8:9]
	s_add_u32 s8, s43, s70
	s_addc_u32 s9, s92, s71
	v_mul_f32_e32 v98, 0xbfb8aa3b, v107
	v_pk_mul_f32 v[100:101], v[94:95], v[98:99] op_sel_hi:[1,0]
	v_pk_mul_f32 v[94:95], v[86:87], v[98:99] op_sel_hi:[1,0]
	v_pk_mul_f32 v[102:103], v[96:97], v[98:99] op_sel_hi:[1,0]
	v_exp_f32_e32 v94, v94
	v_exp_f32_e32 v95, v95
	v_pk_mul_f32 v[96:97], v[88:89], v[98:99] op_sel_hi:[1,0]
	v_exp_f32_e32 v100, v100
	v_exp_f32_e32 v96, v96
	v_exp_f32_e32 v97, v97
	v_pk_fma_f32 v[94:95], v[106:107], v[94:95], v[106:107] op_sel_hi:[0,1,0]
	v_rcp_f32_e32 v94, v94
	v_rcp_f32_e32 v95, v95
	v_exp_f32_e32 v101, v101
	v_pk_fma_f32 v[96:97], v[106:107], v[96:97], v[106:107] op_sel_hi:[0,1,0]
	v_rcp_f32_e32 v96, v96
	v_rcp_f32_e32 v97, v97
	v_pk_mul_f32 v[86:87], v[82:83], v[94:95]
	v_lshlrev_b64 v[82:83], s42, v[146:147]
	v_pk_fma_f32 v[100:101], v[106:107], v[100:101], v[106:107] op_sel_hi:[0,1,0]
	v_min_u32_e32 v82, 1, v82
	v_rcp_f32_e32 v100, v100
	v_rcp_f32_e32 v101, v101
	v_or_b32_e32 v82, v83, v82
	v_pk_mul_f32 v[88:89], v[84:85], v[96:97]
	v_cvt_f32_u32_e32 v84, v182
	v_cvt_f32_u32_e32 v85, v82
	v_exp_f32_e32 v102, v102
	v_exp_f32_e32 v103, v103
	v_pk_mul_f32 v[90:91], v[90:91], v[100:101]
	s_add_u32 s8, s8, s88
	v_cvt_pk_bf16_f32 v82, v90, v91
	v_fmamk_f32 v90, v84, 0x30000000, v209
	v_ldexp_f32 v84, v85, s93
	v_pk_fma_f32 v[102:103], v[106:107], v[102:103], v[106:107] op_sel_hi:[0,1,0]
	v_fmac_f32_e32 v90, 2.0, v84
	v_rcp_f32_e32 v102, v102
	v_rcp_f32_e32 v103, v103
	v_rsq_f32_e32 v91, v90
	s_addc_u32 s9, s9, 0
	s_waitcnt vmcnt(5)
	v_mov_b32_e32 v146, v185
	v_pk_mul_f32 v[92:93], v[92:93], v[102:103]
	s_nop 0
	v_cvt_pk_bf16_f32 v83, v92, v93
	v_cvt_pk_bf16_f32 v84, v86, v87
	v_cvt_pk_bf16_f32 v85, v88, v89
	global_store_dwordx4 v141, v[82:85], s[8:9]
	s_add_u32 s8, s43, s26
	s_addc_u32 s9, s92, s27
	v_mul_f32_e32 v82, 0xbfb8aa3b, v91
	v_pk_mul_f32 v[84:85], v[78:79], v[82:83] op_sel_hi:[1,0]
	v_pk_mul_f32 v[78:79], v[70:71], v[82:83] op_sel_hi:[1,0]
	v_pk_mul_f32 v[86:87], v[80:81], v[82:83] op_sel_hi:[1,0]
	v_exp_f32_e32 v78, v78
	v_exp_f32_e32 v79, v79
	v_pk_mul_f32 v[80:81], v[72:73], v[82:83] op_sel_hi:[1,0]
	v_exp_f32_e32 v84, v84
	v_exp_f32_e32 v80, v80
	v_exp_f32_e32 v81, v81
	v_pk_fma_f32 v[78:79], v[90:91], v[78:79], v[90:91] op_sel_hi:[0,1,0]
	v_rcp_f32_e32 v78, v78
	v_rcp_f32_e32 v79, v79
	v_exp_f32_e32 v85, v85
	v_pk_fma_f32 v[80:81], v[90:91], v[80:81], v[90:91] op_sel_hi:[0,1,0]
	v_rcp_f32_e32 v80, v80
	v_rcp_f32_e32 v81, v81
	v_pk_mul_f32 v[70:71], v[66:67], v[78:79]
	v_lshlrev_b64 v[66:67], s42, v[146:147]
	v_pk_fma_f32 v[84:85], v[90:91], v[84:85], v[90:91] op_sel_hi:[0,1,0]
	v_min_u32_e32 v66, 1, v66
	v_rcp_f32_e32 v84, v84
	v_rcp_f32_e32 v85, v85
	v_or_b32_e32 v66, v67, v66
	v_pk_mul_f32 v[72:73], v[68:69], v[80:81]
	v_cvt_f32_u32_e32 v68, v184
	v_cvt_f32_u32_e32 v69, v66
	v_exp_f32_e32 v86, v86
	v_exp_f32_e32 v87, v87
	v_pk_mul_f32 v[74:75], v[74:75], v[84:85]
	s_add_u32 s8, s8, s88
	v_cvt_pk_bf16_f32 v66, v74, v75
	v_fmamk_f32 v74, v68, 0x30000000, v209
	v_ldexp_f32 v68, v69, s93
	v_pk_fma_f32 v[86:87], v[90:91], v[86:87], v[90:91] op_sel_hi:[0,1,0]
	v_fmac_f32_e32 v74, 2.0, v68
	v_rcp_f32_e32 v86, v86
	v_rcp_f32_e32 v87, v87
	v_rsq_f32_e32 v75, v74
	s_addc_u32 s9, s9, 0
	s_waitcnt vmcnt(5)
	v_mov_b32_e32 v146, v187
	v_pk_mul_f32 v[76:77], v[76:77], v[86:87]
	s_nop 0
	v_cvt_pk_bf16_f32 v67, v76, v77
	v_cvt_pk_bf16_f32 v68, v70, v71
	v_cvt_pk_bf16_f32 v69, v72, v73
	global_store_dwordx4 v141, v[66:69], s[8:9]
	s_add_u32 s8, s43, s22
	s_addc_u32 s9, s92, s82
	v_mul_f32_e32 v66, 0xbfb8aa3b, v75
	v_pk_mul_f32 v[68:69], v[62:63], v[66:67] op_sel_hi:[1,0]
	v_pk_mul_f32 v[62:63], v[54:55], v[66:67] op_sel_hi:[1,0]
	v_pk_mul_f32 v[70:71], v[64:65], v[66:67] op_sel_hi:[1,0]
	v_exp_f32_e32 v62, v62
	v_exp_f32_e32 v63, v63
	v_pk_mul_f32 v[64:65], v[56:57], v[66:67] op_sel_hi:[1,0]
	v_exp_f32_e32 v68, v68
	v_exp_f32_e32 v64, v64
	v_exp_f32_e32 v65, v65
	v_pk_fma_f32 v[62:63], v[74:75], v[62:63], v[74:75] op_sel_hi:[0,1,0]
	v_rcp_f32_e32 v62, v62
	v_rcp_f32_e32 v63, v63
	v_exp_f32_e32 v69, v69
	v_pk_fma_f32 v[64:65], v[74:75], v[64:65], v[74:75] op_sel_hi:[0,1,0]
	v_rcp_f32_e32 v64, v64
	v_rcp_f32_e32 v65, v65
	v_pk_mul_f32 v[54:55], v[50:51], v[62:63]
	v_lshlrev_b64 v[50:51], s42, v[146:147]
	v_pk_fma_f32 v[68:69], v[74:75], v[68:69], v[74:75] op_sel_hi:[0,1,0]
	v_min_u32_e32 v50, 1, v50
	v_rcp_f32_e32 v68, v68
	v_rcp_f32_e32 v69, v69
	v_or_b32_e32 v50, v51, v50
	v_pk_mul_f32 v[56:57], v[52:53], v[64:65]
	v_cvt_f32_u32_e32 v52, v186
	v_cvt_f32_u32_e32 v53, v50
	v_exp_f32_e32 v70, v70
	v_exp_f32_e32 v71, v71
	v_pk_mul_f32 v[58:59], v[58:59], v[68:69]
	s_add_u32 s8, s8, s88
	v_cvt_pk_bf16_f32 v50, v58, v59
	v_fmamk_f32 v58, v52, 0x30000000, v209
	v_ldexp_f32 v52, v53, s93
	v_pk_fma_f32 v[70:71], v[74:75], v[70:71], v[74:75] op_sel_hi:[0,1,0]
	v_fmac_f32_e32 v58, 2.0, v52
	v_rcp_f32_e32 v70, v70
	v_rcp_f32_e32 v71, v71
	v_rsq_f32_e32 v59, v58
	s_addc_u32 s9, s9, 0
	s_waitcnt vmcnt(5)
	v_mov_b32_e32 v146, v189
	v_pk_mul_f32 v[60:61], v[60:61], v[70:71]
	s_nop 0
	v_cvt_pk_bf16_f32 v51, v60, v61
	v_cvt_pk_bf16_f32 v52, v54, v55
	v_cvt_pk_bf16_f32 v53, v56, v57
	global_store_dwordx4 v141, v[50:53], s[8:9]
	s_add_u32 s8, s43, s12
	s_addc_u32 s9, s92, s83
	v_mul_f32_e32 v50, 0xbfb8aa3b, v59
	v_pk_mul_f32 v[52:53], v[46:47], v[50:51] op_sel_hi:[1,0]
	v_pk_mul_f32 v[46:47], v[38:39], v[50:51] op_sel_hi:[1,0]
	v_pk_mul_f32 v[54:55], v[48:49], v[50:51] op_sel_hi:[1,0]
	v_exp_f32_e32 v46, v46
	v_exp_f32_e32 v47, v47
	v_pk_mul_f32 v[48:49], v[40:41], v[50:51] op_sel_hi:[1,0]
	v_exp_f32_e32 v52, v52
	v_exp_f32_e32 v48, v48
	v_exp_f32_e32 v49, v49
	v_pk_fma_f32 v[46:47], v[58:59], v[46:47], v[58:59] op_sel_hi:[0,1,0]
	v_rcp_f32_e32 v46, v46
	v_rcp_f32_e32 v47, v47
	v_exp_f32_e32 v53, v53
	v_pk_fma_f32 v[48:49], v[58:59], v[48:49], v[58:59] op_sel_hi:[0,1,0]
	v_rcp_f32_e32 v48, v48
	v_rcp_f32_e32 v49, v49
	v_pk_mul_f32 v[38:39], v[34:35], v[46:47]
	v_lshlrev_b64 v[34:35], s42, v[146:147]
	v_pk_fma_f32 v[52:53], v[58:59], v[52:53], v[58:59] op_sel_hi:[0,1,0]
	v_min_u32_e32 v34, 1, v34
	v_rcp_f32_e32 v52, v52
	v_rcp_f32_e32 v53, v53
	v_or_b32_e32 v34, v35, v34
	v_pk_mul_f32 v[40:41], v[36:37], v[48:49]
	v_cvt_f32_u32_e32 v36, v188
	v_cvt_f32_u32_e32 v37, v34
	v_exp_f32_e32 v54, v54
	v_exp_f32_e32 v55, v55
	v_pk_mul_f32 v[42:43], v[42:43], v[52:53]
	s_add_u32 s8, s8, s88
	v_cvt_pk_bf16_f32 v34, v42, v43
	v_fmamk_f32 v42, v36, 0x30000000, v209
	v_ldexp_f32 v36, v37, s93
	v_pk_fma_f32 v[54:55], v[58:59], v[54:55], v[58:59] op_sel_hi:[0,1,0]
	v_fmac_f32_e32 v42, 2.0, v36
	v_rcp_f32_e32 v54, v54
	v_rcp_f32_e32 v55, v55
	v_rsq_f32_e32 v43, v42
	s_addc_u32 s9, s9, 0
	s_waitcnt vmcnt(5)
	v_mov_b32_e32 v146, v191
	v_pk_mul_f32 v[44:45], v[44:45], v[54:55]
	s_nop 0
	v_cvt_pk_bf16_f32 v35, v44, v45
	v_cvt_pk_bf16_f32 v36, v38, v39
	v_cvt_pk_bf16_f32 v37, v40, v41
	global_store_dwordx4 v141, v[34:37], s[8:9]
	s_add_u32 s8, s43, s84
	s_addc_u32 s9, s92, s85
	v_mul_f32_e32 v34, 0xbfb8aa3b, v43
	v_pk_mul_f32 v[36:37], v[30:31], v[34:35] op_sel_hi:[1,0]
	v_pk_mul_f32 v[30:31], v[22:23], v[34:35] op_sel_hi:[1,0]
	v_pk_mul_f32 v[38:39], v[32:33], v[34:35] op_sel_hi:[1,0]
	v_exp_f32_e32 v30, v30
	v_exp_f32_e32 v31, v31
	v_pk_mul_f32 v[32:33], v[24:25], v[34:35] op_sel_hi:[1,0]
	v_exp_f32_e32 v36, v36
	v_exp_f32_e32 v32, v32
	v_exp_f32_e32 v33, v33
	v_pk_fma_f32 v[30:31], v[42:43], v[30:31], v[42:43] op_sel_hi:[0,1,0]
	v_rcp_f32_e32 v30, v30
	v_rcp_f32_e32 v31, v31
	v_exp_f32_e32 v37, v37
	v_pk_fma_f32 v[32:33], v[42:43], v[32:33], v[42:43] op_sel_hi:[0,1,0]
	v_rcp_f32_e32 v32, v32
	v_rcp_f32_e32 v33, v33
	v_pk_mul_f32 v[22:23], v[18:19], v[30:31]
	v_lshlrev_b64 v[18:19], s42, v[146:147]
	v_pk_fma_f32 v[36:37], v[42:43], v[36:37], v[42:43] op_sel_hi:[0,1,0]
	v_min_u32_e32 v18, 1, v18
	v_rcp_f32_e32 v36, v36
	v_rcp_f32_e32 v37, v37
	v_or_b32_e32 v18, v19, v18
	v_pk_mul_f32 v[24:25], v[20:21], v[32:33]
	v_cvt_f32_u32_e32 v20, v190
	v_cvt_f32_u32_e32 v21, v18
	v_exp_f32_e32 v38, v38
	v_exp_f32_e32 v39, v39
	v_pk_mul_f32 v[26:27], v[26:27], v[36:37]
	s_add_u32 s8, s8, s88
	v_cvt_pk_bf16_f32 v18, v26, v27
	v_fmamk_f32 v26, v20, 0x30000000, v209
	v_ldexp_f32 v20, v21, s93
	v_pk_fma_f32 v[38:39], v[42:43], v[38:39], v[42:43] op_sel_hi:[0,1,0]
	v_fmac_f32_e32 v26, 2.0, v20
	v_rcp_f32_e32 v38, v38
	v_rcp_f32_e32 v39, v39
	v_rsq_f32_e32 v27, v26
	s_addc_u32 s9, s9, 0
	v_pk_mul_f32 v[28:29], v[28:29], v[38:39]
	s_nop 0
	v_cvt_pk_bf16_f32 v19, v28, v29
	v_cvt_pk_bf16_f32 v20, v22, v23
	v_cvt_pk_bf16_f32 v21, v24, v25
	global_store_dwordx4 v141, v[18:21], s[8:9]
	s_add_u32 s8, s43, s86
	s_addc_u32 s9, s92, s87
	v_mul_f32_e32 v18, 0xbfb8aa3b, v27
	v_pk_mul_f32 v[20:21], v[14:15], v[18:19] op_sel_hi:[1,0]
	v_pk_mul_f32 v[22:23], v[16:17], v[18:19] op_sel_hi:[1,0]
	v_pk_mul_f32 v[14:15], v[6:7], v[18:19] op_sel_hi:[1,0]
	v_pk_mul_f32 v[16:17], v[8:9], v[18:19] op_sel_hi:[1,0]
	v_exp_f32_e32 v20, v20
	v_exp_f32_e32 v21, v21
	v_exp_f32_e32 v22, v22
	v_exp_f32_e32 v23, v23
	v_exp_f32_e32 v14, v14
	v_exp_f32_e32 v15, v15
	v_exp_f32_e32 v16, v16
	v_exp_f32_e32 v17, v17
	v_pk_fma_f32 v[20:21], v[26:27], v[20:21], v[26:27] op_sel_hi:[0,1,0]
	v_pk_fma_f32 v[22:23], v[26:27], v[22:23], v[26:27] op_sel_hi:[0,1,0]
	v_pk_fma_f32 v[14:15], v[26:27], v[14:15], v[26:27] op_sel_hi:[0,1,0]
	v_pk_fma_f32 v[16:17], v[26:27], v[16:17], v[26:27] op_sel_hi:[0,1,0]
	v_rcp_f32_e32 v20, v20
	v_rcp_f32_e32 v21, v21
	v_rcp_f32_e32 v22, v22
	v_rcp_f32_e32 v23, v23
	v_rcp_f32_e32 v14, v14
	v_rcp_f32_e32 v15, v15
	v_rcp_f32_e32 v16, v16
	v_rcp_f32_e32 v17, v17
	s_add_u32 s8, s8, s88
	s_addc_u32 s9, s9, 0
	v_pk_mul_f32 v[10:11], v[10:11], v[20:21]
	v_pk_mul_f32 v[12:13], v[12:13], v[22:23]
	v_pk_mul_f32 v[6:7], v[2:3], v[14:15]
	v_pk_mul_f32 v[8:9], v[4:5], v[16:17]
	v_cvt_pk_bf16_f32 v2, v10, v11
	v_cvt_pk_bf16_f32 v3, v12, v13
	v_cvt_pk_bf16_f32 v4, v6, v7
	s_andn2_b64 vcc, exec, s[34:35]
	v_cvt_pk_bf16_f32 v5, v8, v9
	global_store_dwordx4 v141, v[2:5], s[8:9]
	s_mov_b64 s[8:9], -1
	s_cbranch_vccnz .LBB0_293
	s_andn2_b64 vcc, exec, s[44:45]
	s_cbranch_vccnz .LBB0_292
	s_barrier
	s_branch .LBB0_292

.LBB0_1880:
	v_add_u32_e32 v139, 0x10000, v136
	ds_read_b128 v[140:143], v139
	ds_read_b128 v[154:157], v139 offset:1024
	ds_read_b128 v[170:173], v139 offset:2048
	ds_read_b128 v[174:177], v139 offset:3072
	v_add_u32_e32 v139, 0x14000, v136
	ds_read_b128 v[178:181], v139
	ds_read_b128 v[182:185], v139 offset:1024
	ds_read_b128 v[186:189], v139 offset:2048
	ds_read_b128 v[190:193], v139 offset:3072
	s_add_i32 s42, vcc_lo, 0xfff80080
	s_cmp_eq_u32 s94, 28
	s_cselect_b32 s52, s8, s42
	s_cselect_b32 s96, s9, vcc_hi
	s_or_b32 s95, s52, 0x80
	s_mov_b32 m0, s72
	ds_read_b128 v[194:197], v137
	ds_read_b128 v[198:201], v137 offset:1024
	ds_read_b128 v[202:205], v137 offset:2048
	ds_read_b128 v[228:231], v137 offset:3072
	ds_read_b128 v[232:235], v137 offset:4096
	ds_read_b128 v[236:239], v137 offset:5120
	ds_read_b128 v[240:243], v137 offset:6144
	ds_read_b128 v[244:247], v137 offset:7168
	buffer_load_dwordx4 v132, s[60:63], vcc_lo offen lds
	s_mov_b32 m0, s47
	s_nop 0
	buffer_load_dwordx4 v134, s[60:63], vcc_lo offen lds
	s_waitcnt vmcnt(8)
	s_waitcnt lgkmcnt(0)
	s_setprio 1
	s_barrier
	v_mfma_f32_16x16x32_bf16 v[114:117], v[140:143], v[194:197], v[114:117]
	v_mfma_f32_16x16x32_bf16 v[110:113], v[170:173], v[194:197], v[110:113]
	v_mfma_f32_16x16x32_bf16 v[106:109], v[140:143], v[202:205], v[106:109]
	v_mfma_f32_16x16x32_bf16 v[102:105], v[170:173], v[202:205], v[102:105]
	v_mfma_f32_16x16x32_bf16 v[94:97], v[140:143], v[232:235], v[94:97]
	v_mfma_f32_16x16x32_bf16 v[86:89], v[170:173], v[232:235], v[86:89]
	v_mfma_f32_16x16x32_bf16 v[78:81], v[140:143], v[240:243], v[78:81]
	v_mfma_f32_16x16x32_bf16 v[70:73], v[170:173], v[240:243], v[70:73]
	v_mfma_f32_16x16x32_bf16 v[114:117], v[154:157], v[198:201], v[114:117]
	v_mfma_f32_16x16x32_bf16 v[110:113], v[174:177], v[198:201], v[110:113]
	v_mfma_f32_16x16x32_bf16 v[106:109], v[154:157], v[228:231], v[106:109]
	v_mfma_f32_16x16x32_bf16 v[102:105], v[174:177], v[228:231], v[102:105]
	v_mfma_f32_16x16x32_bf16 v[94:97], v[154:157], v[236:239], v[94:97]
	v_mfma_f32_16x16x32_bf16 v[86:89], v[174:177], v[236:239], v[86:89]
	v_mfma_f32_16x16x32_bf16 v[78:81], v[154:157], v[244:247], v[78:81]
	v_mfma_f32_16x16x32_bf16 v[70:73], v[174:177], v[244:247], v[70:73]
	v_mfma_f32_16x16x32_bf16 v[126:129], v[178:181], v[194:197], v[126:129]
	v_mfma_f32_16x16x32_bf16 v[122:125], v[186:189], v[194:197], v[122:125]
	v_mfma_f32_16x16x32_bf16 v[118:121], v[178:181], v[202:205], v[118:121]
	v_mfma_f32_16x16x32_bf16 v[98:101], v[186:189], v[202:205], v[98:101]
	v_mfma_f32_16x16x32_bf16 v[90:93], v[178:181], v[232:235], v[90:93]
	v_mfma_f32_16x16x32_bf16 v[82:85], v[186:189], v[232:235], v[82:85]
	v_mfma_f32_16x16x32_bf16 v[74:77], v[178:181], v[240:243], v[74:77]
	v_mfma_f32_16x16x32_bf16 v[66:69], v[186:189], v[240:243], v[66:69]
	v_mfma_f32_16x16x32_bf16 v[126:129], v[182:185], v[198:201], v[126:129]
	v_mfma_f32_16x16x32_bf16 v[122:125], v[190:193], v[198:201], v[122:125]
	v_mfma_f32_16x16x32_bf16 v[118:121], v[182:185], v[228:231], v[118:121]
	v_mfma_f32_16x16x32_bf16 v[98:101], v[190:193], v[228:231], v[98:101]
	v_mfma_f32_16x16x32_bf16 v[90:93], v[182:185], v[236:239], v[90:93]
	v_mfma_f32_16x16x32_bf16 v[82:85], v[190:193], v[236:239], v[82:85]
	v_mfma_f32_16x16x32_bf16 v[74:77], v[182:185], v[244:247], v[74:77]
	v_mfma_f32_16x16x32_bf16 v[66:69], v[190:193], v[244:247], v[66:69]
	s_barrier
	s_setprio 0
	s_mov_b32 m0, s13
	s_mov_b32 s42, s62
	s_mov_b32 s43, s63
	ds_read_b128 v[194:197], v137 offset:16384
	ds_read_b128 v[198:201], v137 offset:17408
	ds_read_b128 v[202:205], v137 offset:18432
	ds_read_b128 v[228:231], v137 offset:19456
	ds_read_b128 v[232:235], v137 offset:20480
	ds_read_b128 v[236:239], v137 offset:21504
	ds_read_b128 v[240:243], v137 offset:22528
	ds_read_b128 v[244:247], v137 offset:23552
	buffer_load_dwordx4 v133, s[40:43], s96 offen lds
	s_mov_b32 m0, s14
	s_add_i32 s53, s96, 0x80000
	buffer_load_dwordx4 v135, s[40:43], s96 offen lds
	s_mov_b32 m0, s15
	s_nop 0
	buffer_load_dwordx4 v133, s[40:43], s53 offen lds
	s_mov_b32 m0, s16
	s_nop 0
	buffer_load_dwordx4 v135, s[40:43], s53 offen lds
	s_mov_b32 m0, s2
	s_nop 0
	buffer_load_dwordx4 v132, s[60:63], s52 offen lds
	s_mov_b32 m0, s21
	s_nop 0
	buffer_load_dwordx4 v134, s[60:63], s52 offen lds
	s_waitcnt vmcnt(8)
	s_waitcnt lgkmcnt(0)
	s_setprio 1
	s_barrier
	v_mfma_f32_16x16x32_bf16 v[62:65], v[140:143], v[194:197], v[62:65]
	v_mfma_f32_16x16x32_bf16 v[54:57], v[170:173], v[194:197], v[54:57]
	v_mfma_f32_16x16x32_bf16 v[46:49], v[140:143], v[202:205], v[46:49]
	v_mfma_f32_16x16x32_bf16 v[38:41], v[170:173], v[202:205], v[38:41]
	v_mfma_f32_16x16x32_bf16 v[30:33], v[140:143], v[232:235], v[30:33]
	v_mfma_f32_16x16x32_bf16 v[22:25], v[170:173], v[232:235], v[22:25]
	v_mfma_f32_16x16x32_bf16 v[14:17], v[140:143], v[240:243], v[14:17]
	v_mfma_f32_16x16x32_bf16 v[6:9], v[170:173], v[240:243], v[6:9]
	v_mfma_f32_16x16x32_bf16 v[62:65], v[154:157], v[198:201], v[62:65]
	v_mfma_f32_16x16x32_bf16 v[54:57], v[174:177], v[198:201], v[54:57]
	v_mfma_f32_16x16x32_bf16 v[46:49], v[154:157], v[228:231], v[46:49]
	v_mfma_f32_16x16x32_bf16 v[38:41], v[174:177], v[228:231], v[38:41]
	v_mfma_f32_16x16x32_bf16 v[30:33], v[154:157], v[236:239], v[30:33]
	v_mfma_f32_16x16x32_bf16 v[22:25], v[174:177], v[236:239], v[22:25]
	v_mfma_f32_16x16x32_bf16 v[14:17], v[154:157], v[244:247], v[14:17]
	v_mfma_f32_16x16x32_bf16 v[6:9], v[174:177], v[244:247], v[6:9]
	v_mfma_f32_16x16x32_bf16 v[58:61], v[178:181], v[194:197], v[58:61]
	v_mfma_f32_16x16x32_bf16 v[50:53], v[186:189], v[194:197], v[50:53]
	v_mfma_f32_16x16x32_bf16 v[42:45], v[178:181], v[202:205], v[42:45]
	v_mfma_f32_16x16x32_bf16 v[34:37], v[186:189], v[202:205], v[34:37]
	v_mfma_f32_16x16x32_bf16 v[26:29], v[178:181], v[232:235], v[26:29]
	v_mfma_f32_16x16x32_bf16 v[18:21], v[186:189], v[232:235], v[18:21]
	v_mfma_f32_16x16x32_bf16 v[10:13], v[178:181], v[240:243], v[10:13]
	v_mfma_f32_16x16x32_bf16 v[2:5], v[186:189], v[240:243], v[2:5]
	v_mfma_f32_16x16x32_bf16 v[58:61], v[182:185], v[198:201], v[58:61]
	v_mfma_f32_16x16x32_bf16 v[50:53], v[190:193], v[198:201], v[50:53]
	v_mfma_f32_16x16x32_bf16 v[42:45], v[182:185], v[228:231], v[42:45]
	v_mfma_f32_16x16x32_bf16 v[34:37], v[190:193], v[228:231], v[34:37]
	v_mfma_f32_16x16x32_bf16 v[26:29], v[182:185], v[236:239], v[26:29]
	v_mfma_f32_16x16x32_bf16 v[18:21], v[190:193], v[236:239], v[18:21]
	v_mfma_f32_16x16x32_bf16 v[10:13], v[182:185], v[244:247], v[10:13]
	v_mfma_f32_16x16x32_bf16 v[2:5], v[190:193], v[244:247], v[2:5]
	s_barrier
	s_setprio 0
	v_add_u32_e32 v139, 0x18000, v136
	ds_read_b128 v[140:143], v139
	ds_read_b128 v[154:157], v139 offset:1024
	ds_read_b128 v[170:173], v139 offset:2048
	ds_read_b128 v[174:177], v139 offset:3072
	v_add_u32_e32 v139, 0x1c000, v136
	ds_read_b128 v[178:181], v139
	ds_read_b128 v[182:185], v139 offset:1024
	ds_read_b128 v[186:189], v139 offset:2048
	ds_read_b128 v[190:193], v139 offset:3072
	s_add_i32 s52, s52, 0x80000
	s_mov_b32 m0, s23
	ds_read_b128 v[194:197], v137 offset:32768
	ds_read_b128 v[198:201], v137 offset:33792
	ds_read_b128 v[202:205], v137 offset:34816
	ds_read_b128 v[228:231], v137 offset:35840
	ds_read_b128 v[232:235], v137 offset:36864
	ds_read_b128 v[236:239], v137 offset:37888
	ds_read_b128 v[240:243], v137 offset:38912
	ds_read_b128 v[244:247], v137 offset:39936
	buffer_load_dwordx4 v132, s[60:63], s52 offen lds
	s_mov_b32 m0, s24
	s_nop 0
	buffer_load_dwordx4 v134, s[60:63], s52 offen lds
	s_waitcnt vmcnt(8)
	s_waitcnt lgkmcnt(0)
	s_setprio 1
	s_barrier
	v_mfma_f32_16x16x32_bf16 v[114:117], v[140:143], v[194:197], v[114:117]
	v_mfma_f32_16x16x32_bf16 v[110:113], v[170:173], v[194:197], v[110:113]
	v_mfma_f32_16x16x32_bf16 v[106:109], v[140:143], v[202:205], v[106:109]
	v_mfma_f32_16x16x32_bf16 v[102:105], v[170:173], v[202:205], v[102:105]
	v_mfma_f32_16x16x32_bf16 v[94:97], v[140:143], v[232:235], v[94:97]
	v_mfma_f32_16x16x32_bf16 v[86:89], v[170:173], v[232:235], v[86:89]
	v_mfma_f32_16x16x32_bf16 v[78:81], v[140:143], v[240:243], v[78:81]
	v_mfma_f32_16x16x32_bf16 v[70:73], v[170:173], v[240:243], v[70:73]
	v_mfma_f32_16x16x32_bf16 v[114:117], v[154:157], v[198:201], v[114:117]
	v_mfma_f32_16x16x32_bf16 v[110:113], v[174:177], v[198:201], v[110:113]
	v_mfma_f32_16x16x32_bf16 v[106:109], v[154:157], v[228:231], v[106:109]
	v_mfma_f32_16x16x32_bf16 v[102:105], v[174:177], v[228:231], v[102:105]
	v_mfma_f32_16x16x32_bf16 v[94:97], v[154:157], v[236:239], v[94:97]
	v_mfma_f32_16x16x32_bf16 v[86:89], v[174:177], v[236:239], v[86:89]
	v_mfma_f32_16x16x32_bf16 v[78:81], v[154:157], v[244:247], v[78:81]
	v_mfma_f32_16x16x32_bf16 v[70:73], v[174:177], v[244:247], v[70:73]
	v_mfma_f32_16x16x32_bf16 v[126:129], v[178:181], v[194:197], v[126:129]
	v_mfma_f32_16x16x32_bf16 v[122:125], v[186:189], v[194:197], v[122:125]
	v_mfma_f32_16x16x32_bf16 v[118:121], v[178:181], v[202:205], v[118:121]
	v_mfma_f32_16x16x32_bf16 v[98:101], v[186:189], v[202:205], v[98:101]
	v_mfma_f32_16x16x32_bf16 v[90:93], v[178:181], v[232:235], v[90:93]
	v_mfma_f32_16x16x32_bf16 v[82:85], v[186:189], v[232:235], v[82:85]
	v_mfma_f32_16x16x32_bf16 v[74:77], v[178:181], v[240:243], v[74:77]
	v_mfma_f32_16x16x32_bf16 v[66:69], v[186:189], v[240:243], v[66:69]
	v_mfma_f32_16x16x32_bf16 v[126:129], v[182:185], v[198:201], v[126:129]
	v_mfma_f32_16x16x32_bf16 v[122:125], v[190:193], v[198:201], v[122:125]
	v_mfma_f32_16x16x32_bf16 v[118:121], v[182:185], v[228:231], v[118:121]
	v_mfma_f32_16x16x32_bf16 v[98:101], v[190:193], v[228:231], v[98:101]
	v_mfma_f32_16x16x32_bf16 v[90:93], v[182:185], v[236:239], v[90:93]
	v_mfma_f32_16x16x32_bf16 v[82:85], v[190:193], v[236:239], v[82:85]
	v_mfma_f32_16x16x32_bf16 v[74:77], v[182:185], v[244:247], v[74:77]
	v_mfma_f32_16x16x32_bf16 v[66:69], v[190:193], v[244:247], v[66:69]
	s_barrier
	s_setprio 0
	s_mov_b32 m0, s31
	s_or_b32 s52, s96, 0x80
	ds_read_b128 v[194:197], v137 offset:49152
	ds_read_b128 v[198:201], v137 offset:50176
	ds_read_b128 v[202:205], v137 offset:51200
	ds_read_b128 v[228:231], v137 offset:52224
	ds_read_b128 v[232:235], v137 offset:53248
	ds_read_b128 v[236:239], v137 offset:54272
	ds_read_b128 v[240:243], v137 offset:55296
	ds_read_b128 v[244:247], v137 offset:56320
	buffer_load_dwordx4 v133, s[40:43], s52 offen lds
	s_mov_b32 m0, s33
	s_add_i32 s96, s96, 0x80080
	buffer_load_dwordx4 v135, s[40:43], s52 offen lds
	s_mov_b32 m0, s36
	s_nop 0
	buffer_load_dwordx4 v133, s[40:43], s96 offen lds
	s_mov_b32 m0, s37
	s_nop 0
	buffer_load_dwordx4 v135, s[40:43], s96 offen lds
	s_mov_b32 m0, s34
	s_nop 0
	buffer_load_dwordx4 v132, s[60:63], s95 offen lds
	s_mov_b32 m0, s35
	s_nop 0
	buffer_load_dwordx4 v134, s[60:63], s95 offen lds
	s_waitcnt vmcnt(8)
	s_waitcnt lgkmcnt(0)
	s_setprio 1
	s_barrier
	v_mfma_f32_16x16x32_bf16 v[62:65], v[140:143], v[194:197], v[62:65]
	v_mfma_f32_16x16x32_bf16 v[54:57], v[170:173], v[194:197], v[54:57]
	v_mfma_f32_16x16x32_bf16 v[46:49], v[140:143], v[202:205], v[46:49]
	v_mfma_f32_16x16x32_bf16 v[38:41], v[170:173], v[202:205], v[38:41]
	v_mfma_f32_16x16x32_bf16 v[30:33], v[140:143], v[232:235], v[30:33]
	v_mfma_f32_16x16x32_bf16 v[22:25], v[170:173], v[232:235], v[22:25]
	v_mfma_f32_16x16x32_bf16 v[14:17], v[140:143], v[240:243], v[14:17]
	v_mfma_f32_16x16x32_bf16 v[6:9], v[170:173], v[240:243], v[6:9]
	v_mfma_f32_16x16x32_bf16 v[62:65], v[154:157], v[198:201], v[62:65]
	v_mfma_f32_16x16x32_bf16 v[54:57], v[174:177], v[198:201], v[54:57]
	v_mfma_f32_16x16x32_bf16 v[46:49], v[154:157], v[228:231], v[46:49]
	v_mfma_f32_16x16x32_bf16 v[38:41], v[174:177], v[228:231], v[38:41]
	v_mfma_f32_16x16x32_bf16 v[30:33], v[154:157], v[236:239], v[30:33]
	v_mfma_f32_16x16x32_bf16 v[22:25], v[174:177], v[236:239], v[22:25]
	v_mfma_f32_16x16x32_bf16 v[14:17], v[154:157], v[244:247], v[14:17]
	v_mfma_f32_16x16x32_bf16 v[6:9], v[174:177], v[244:247], v[6:9]
	v_mfma_f32_16x16x32_bf16 v[58:61], v[178:181], v[194:197], v[58:61]
	v_mfma_f32_16x16x32_bf16 v[50:53], v[186:189], v[194:197], v[50:53]
	v_mfma_f32_16x16x32_bf16 v[42:45], v[178:181], v[202:205], v[42:45]
	v_mfma_f32_16x16x32_bf16 v[34:37], v[186:189], v[202:205], v[34:37]
	v_mfma_f32_16x16x32_bf16 v[26:29], v[178:181], v[232:235], v[26:29]
	v_mfma_f32_16x16x32_bf16 v[18:21], v[186:189], v[232:235], v[18:21]
	v_mfma_f32_16x16x32_bf16 v[10:13], v[178:181], v[240:243], v[10:13]
	v_mfma_f32_16x16x32_bf16 v[2:5], v[186:189], v[240:243], v[2:5]
	v_mfma_f32_16x16x32_bf16 v[58:61], v[182:185], v[198:201], v[58:61]
	v_mfma_f32_16x16x32_bf16 v[50:53], v[190:193], v[198:201], v[50:53]
	v_mfma_f32_16x16x32_bf16 v[42:45], v[182:185], v[228:231], v[42:45]
	v_mfma_f32_16x16x32_bf16 v[34:37], v[190:193], v[228:231], v[34:37]
	v_mfma_f32_16x16x32_bf16 v[26:29], v[182:185], v[236:239], v[26:29]
	v_mfma_f32_16x16x32_bf16 v[18:21], v[190:193], v[236:239], v[18:21]
	v_mfma_f32_16x16x32_bf16 v[10:13], v[182:185], v[244:247], v[10:13]
	v_mfma_f32_16x16x32_bf16 v[2:5], v[190:193], v[244:247], v[2:5]
	s_barrier
	s_setprio 0
	s_add_i32 s94, s94, 2
	s_addk_i32 vcc_lo, 0x100
	s_addk_i32 vcc_hi, 0x100
	s_cmp_gt_u32 s94, 29
	s_cbranch_scc0 .LBB0_1880
	s_lshl_b32 s8, s93, 8
	s_add_i32 s8, s8, s46
	s_ashr_i32 s9, s8, 31
	v_lshl_add_u64 v[140:141], s[8:9], 3, v[130:131]
	global_load_dwordx2 v[142:143], v[140:141], off
	global_load_dwordx2 v[144:145], v[140:141], off offset:128
	global_load_dwordx2 v[176:177], v[140:141], off offset:256
	global_load_dwordx2 v[182:183], v[140:141], off offset:384
	global_load_dwordx2 v[184:185], v[140:141], off offset:1024
	global_load_dwordx2 v[186:187], v[140:141], off offset:1152
	global_load_dwordx2 v[188:189], v[140:141], off offset:1280
	global_load_dwordx2 v[190:191], v[140:141], off offset:1408
	s_and_b64 vcc, exec, s[64:65]
	s_cbranch_vccz .LBB0_1883
	s_barrier
.LBB0_1883:
	v_pk_mul_f32 v[154:155], v[114:115], v[126:127]
	v_pk_mul_f32 v[156:157], v[112:113], v[124:125]
	v_pk_mul_f32 v[170:171], v[110:111], v[122:123]
	v_pk_mul_f32 v[172:173], v[108:109], v[120:121]
	v_pk_mul_f32 v[174:175], v[106:107], v[118:119]
	s_flbit_i32_b32 s8, 0
	s_min_u32 s42, s8, 32
	s_mul_i32 s8, s93, 0x58
	s_sub_i32 s93, 32, s42
	v_pk_mul_f32 v[128:129], v[116:117], v[128:129]
	s_lshl_b32 s9, s90, 1
	s_or_b32 s9, s9, s73
	s_add_i32 s8, s9, s8
	s_ashr_i32 s9, s8, 31
	s_lshl_b64 s[8:9], s[8:9], 15
	s_add_u32 s43, s25, s8
	s_addc_u32 s90, s30, s9
	s_add_u32 s8, s43, s66
	s_addc_u32 s9, s90, s67
	s_add_u32 s8, s8, s88
	s_addc_u32 s9, s9, 0
	v_pk_mul_f32 v[98:99], v[102:103], v[98:99]
	v_pk_mul_f32 v[100:101], v[104:105], v[100:101]
	v_pk_mul_f32 v[90:91], v[94:95], v[90:91]
	v_pk_mul_f32 v[92:93], v[96:97], v[92:93]
	v_pk_mul_f32 v[82:83], v[86:87], v[82:83]
	v_pk_mul_f32 v[84:85], v[88:89], v[84:85]
	v_pk_mul_f32 v[74:75], v[78:79], v[74:75]
	v_pk_mul_f32 v[76:77], v[80:81], v[76:77]
	v_pk_mul_f32 v[66:67], v[70:71], v[66:67]
	v_pk_mul_f32 v[68:69], v[72:73], v[68:69]
	v_pk_mul_f32 v[58:59], v[62:63], v[58:59]
	v_pk_mul_f32 v[60:61], v[64:65], v[60:61]
	v_pk_mul_f32 v[50:51], v[54:55], v[50:51]
	v_pk_mul_f32 v[52:53], v[56:57], v[52:53]
	v_pk_mul_f32 v[42:43], v[46:47], v[42:43]
	v_pk_mul_f32 v[44:45], v[48:49], v[44:45]
	v_pk_mul_f32 v[34:35], v[38:39], v[34:35]
	v_pk_mul_f32 v[36:37], v[40:41], v[36:37]
	v_pk_mul_f32 v[26:27], v[30:31], v[26:27]
	v_pk_mul_f32 v[28:29], v[32:33], v[28:29]
	v_pk_mul_f32 v[18:19], v[22:23], v[18:19]
	v_pk_mul_f32 v[20:21], v[24:25], v[20:21]
	v_pk_mul_f32 v[12:13], v[16:17], v[12:13]
	v_pk_mul_f32 v[10:11], v[14:15], v[10:11]
	v_pk_mul_f32 v[4:5], v[8:9], v[4:5]
	v_pk_mul_f32 v[2:3], v[6:7], v[2:3]
	v_readlane_b32 s96, v252, 46
	s_waitcnt vmcnt(0)
	v_cvt_f32_u32_e32 v139, v142
	v_mov_b32_e32 v146, v143
	v_lshlrev_b64 v[140:141], s42, v[146:147]
	v_min_u32_e32 v140, 1, v140
	v_mov_b32_e32 v146, v145
	v_or_b32_e32 v141, v141, v140
	v_lshlrev_b64 v[142:143], s42, v[146:147]
	v_fmamk_f32 v140, v139, 0x30000000, v209
	v_cvt_f32_u32_e32 v139, v141
	v_min_u32_e32 v145, 1, v142
	v_or_b32_e32 v141, v143, v145
	v_cvt_f32_u32_e32 v144, v144
	v_cvt_f32_u32_e32 v141, v141
	v_ldexp_f32 v139, v139, s93
	v_fmac_f32_e32 v140, 2.0, v139
	v_rsq_f32_e32 v139, v140
	v_fmamk_f32 v142, v144, 0x30000000, v209
	v_ldexp_f32 v141, v141, s93
	v_fmac_f32_e32 v142, 2.0, v141
	v_rsq_f32_e32 v141, v142
	v_mul_f32_e32 v144, 0xbfb8aa3b, v139
	v_pk_mul_f32 v[114:115], v[114:115], v[144:145] op_sel_hi:[1,0]
	v_pk_mul_f32 v[116:117], v[116:117], v[144:145] op_sel_hi:[1,0]
	v_exp_f32_e32 v114, v114
	v_exp_f32_e32 v115, v115
	v_pk_mul_f32 v[110:111], v[110:111], v[144:145] op_sel_hi:[1,0]
	v_pk_mul_f32 v[112:113], v[112:113], v[144:145] op_sel_hi:[1,0]
	v_mul_f32_e32 v144, 0xbfb8aa3b, v141
	v_exp_f32_e32 v116, v116
	v_exp_f32_e32 v117, v117
	v_exp_f32_e32 v110, v110
	v_exp_f32_e32 v111, v111
	v_exp_f32_e32 v112, v112
	v_exp_f32_e32 v113, v113
	v_pk_mul_f32 v[178:179], v[102:103], v[144:145] op_sel_hi:[1,0]
	v_pk_mul_f32 v[106:107], v[106:107], v[144:145] op_sel_hi:[1,0]
	v_exp_f32_e32 v178, v178
	v_exp_f32_e32 v179, v179
	v_pk_mul_f32 v[108:109], v[108:109], v[144:145] op_sel_hi:[1,0]
	v_pk_mul_f32 v[144:145], v[104:105], v[144:145] op_sel_hi:[1,0]
	v_exp_f32_e32 v106, v106
	v_exp_f32_e32 v107, v107
	v_pk_fma_f32 v[114:115], v[140:141], v[114:115], v[140:141] op_sel_hi:[0,1,0]
	v_exp_f32_e32 v108, v108
	v_exp_f32_e32 v109, v109
	v_exp_f32_e32 v144, v144
	v_exp_f32_e32 v145, v145
	v_pk_fma_f32 v[116:117], v[140:141], v[116:117], v[140:141] op_sel_hi:[0,1,0]
	v_rcp_f32_e32 v114, v114
	v_rcp_f32_e32 v115, v115
	v_pk_fma_f32 v[110:111], v[140:141], v[110:111], v[140:141] op_sel_hi:[0,1,0]
	v_pk_fma_f32 v[112:113], v[140:141], v[112:113], v[140:141] op_sel_hi:[0,1,0]
	v_rcp_f32_e32 v116, v116
	v_rcp_f32_e32 v117, v117
	v_rcp_f32_e32 v110, v110
	v_rcp_f32_e32 v111, v111
	v_rcp_f32_e32 v112, v112
	v_rcp_f32_e32 v113, v113
	v_pk_fma_f32 v[140:141], v[142:143], v[178:179], v[142:143] op_sel_hi:[0,1,0]
	v_pk_fma_f32 v[106:107], v[142:143], v[106:107], v[142:143] op_sel_hi:[0,1,0]
	v_rcp_f32_e32 v140, v140
	v_rcp_f32_e32 v141, v141
	v_pk_fma_f32 v[108:109], v[142:143], v[108:109], v[142:143] op_sel_hi:[0,1,0]
	v_pk_fma_f32 v[142:143], v[142:143], v[144:145], v[142:143] op_sel_hi:[0,1,0]
	v_rcp_f32_e32 v144, v106
	v_rcp_f32_e32 v145, v107
	v_pk_mul_f32 v[106:107], v[154:155], v[114:115]
	v_rcp_f32_e32 v178, v108
	v_rcp_f32_e32 v179, v109
	v_pk_mul_f32 v[108:109], v[128:129], v[116:117]
	v_cvt_pk_bf16_f32 v106, v106, v107
	v_pk_mul_f32 v[110:111], v[170:171], v[110:111]
	v_cvt_pk_bf16_f32 v107, v108, v109
	v_pk_mul_f32 v[112:113], v[156:157], v[112:113]
	v_cvt_pk_bf16_f32 v108, v110, v111
	v_mov_b32_e32 v146, v177
	v_cvt_pk_bf16_f32 v109, v112, v113
	global_store_dwordx4 v138, v[106:109], s[8:9]
	v_pk_mul_f32 v[102:103], v[98:99], v[140:141]
	v_lshlrev_b64 v[98:99], s42, v[146:147]
	v_rcp_f32_e32 v106, v142
	v_rcp_f32_e32 v107, v143
	v_min_u32_e32 v98, 1, v98
	v_or_b32_e32 v98, v99, v98
	s_add_u32 s8, s43, s68
	v_pk_mul_f32 v[104:105], v[100:101], v[106:107]
	v_cvt_f32_u32_e32 v100, v176
	v_cvt_f32_u32_e32 v101, v98
	s_addc_u32 s9, s90, s69
	s_add_u32 s8, s8, s88
	v_fmamk_f32 v106, v100, 0x30000000, v209
	v_ldexp_f32 v100, v101, s93
	v_fmac_f32_e32 v106, 2.0, v100
	v_rsq_f32_e32 v107, v106
	v_pk_mul_f32 v[110:111], v[174:175], v[144:145]
	s_addc_u32 s9, s9, 0
	v_cvt_pk_bf16_f32 v98, v110, v111
	v_pk_mul_f32 v[112:113], v[172:173], v[178:179]
	v_mov_b32_e32 v146, v183
	v_cvt_pk_bf16_f32 v99, v112, v113
	v_cvt_pk_bf16_f32 v100, v102, v103
	v_cvt_pk_bf16_f32 v101, v104, v105
	global_store_dwordx4 v138, v[98:101], s[8:9]
	s_add_u32 s8, s43, s70
	s_addc_u32 s9, s90, s71
	v_mul_f32_e32 v98, 0xbfb8aa3b, v107
	v_pk_mul_f32 v[100:101], v[94:95], v[98:99] op_sel_hi:[1,0]
	v_pk_mul_f32 v[94:95], v[86:87], v[98:99] op_sel_hi:[1,0]
	v_pk_mul_f32 v[102:103], v[96:97], v[98:99] op_sel_hi:[1,0]
	v_exp_f32_e32 v94, v94
	v_exp_f32_e32 v95, v95
	v_pk_mul_f32 v[96:97], v[88:89], v[98:99] op_sel_hi:[1,0]
	v_exp_f32_e32 v100, v100
	v_exp_f32_e32 v96, v96
	v_exp_f32_e32 v97, v97
	v_pk_fma_f32 v[94:95], v[106:107], v[94:95], v[106:107] op_sel_hi:[0,1,0]
	v_rcp_f32_e32 v94, v94
	v_rcp_f32_e32 v95, v95
	v_exp_f32_e32 v101, v101
	v_pk_fma_f32 v[96:97], v[106:107], v[96:97], v[106:107] op_sel_hi:[0,1,0]
	v_rcp_f32_e32 v96, v96
	v_rcp_f32_e32 v97, v97
	v_pk_mul_f32 v[86:87], v[82:83], v[94:95]
	v_lshlrev_b64 v[82:83], s42, v[146:147]
	v_pk_fma_f32 v[100:101], v[106:107], v[100:101], v[106:107] op_sel_hi:[0,1,0]
	v_min_u32_e32 v82, 1, v82
	v_rcp_f32_e32 v100, v100
	v_rcp_f32_e32 v101, v101
	v_or_b32_e32 v82, v83, v82
	v_pk_mul_f32 v[88:89], v[84:85], v[96:97]
	v_cvt_f32_u32_e32 v84, v182
	v_cvt_f32_u32_e32 v85, v82
	v_exp_f32_e32 v102, v102
	v_exp_f32_e32 v103, v103
	v_pk_mul_f32 v[90:91], v[90:91], v[100:101]
	s_add_u32 s8, s8, s88
	v_cvt_pk_bf16_f32 v82, v90, v91
	v_fmamk_f32 v90, v84, 0x30000000, v209
	v_ldexp_f32 v84, v85, s93
	v_pk_fma_f32 v[102:103], v[106:107], v[102:103], v[106:107] op_sel_hi:[0,1,0]
	v_fmac_f32_e32 v90, 2.0, v84
	v_rcp_f32_e32 v102, v102
	v_rcp_f32_e32 v103, v103
	v_rsq_f32_e32 v91, v90
	s_addc_u32 s9, s9, 0
	v_mov_b32_e32 v146, v185
	v_pk_mul_f32 v[92:93], v[92:93], v[102:103]
	s_nop 0
	v_cvt_pk_bf16_f32 v83, v92, v93
	v_cvt_pk_bf16_f32 v84, v86, v87
	v_cvt_pk_bf16_f32 v85, v88, v89
	global_store_dwordx4 v138, v[82:85], s[8:9]
	s_add_u32 s8, s43, s26
	s_addc_u32 s9, s90, s27
	v_mul_f32_e32 v82, 0xbfb8aa3b, v91
	v_pk_mul_f32 v[84:85], v[78:79], v[82:83] op_sel_hi:[1,0]
	v_pk_mul_f32 v[78:79], v[70:71], v[82:83] op_sel_hi:[1,0]
	v_pk_mul_f32 v[86:87], v[80:81], v[82:83] op_sel_hi:[1,0]
	v_exp_f32_e32 v78, v78
	v_exp_f32_e32 v79, v79
	v_pk_mul_f32 v[80:81], v[72:73], v[82:83] op_sel_hi:[1,0]
	v_exp_f32_e32 v84, v84
	v_exp_f32_e32 v80, v80
	v_exp_f32_e32 v81, v81
	v_pk_fma_f32 v[78:79], v[90:91], v[78:79], v[90:91] op_sel_hi:[0,1,0]
	v_rcp_f32_e32 v78, v78
	v_rcp_f32_e32 v79, v79
	v_exp_f32_e32 v85, v85
	v_pk_fma_f32 v[80:81], v[90:91], v[80:81], v[90:91] op_sel_hi:[0,1,0]
	v_rcp_f32_e32 v80, v80
	v_rcp_f32_e32 v81, v81
	v_pk_mul_f32 v[70:71], v[66:67], v[78:79]
	v_lshlrev_b64 v[66:67], s42, v[146:147]
	v_pk_fma_f32 v[84:85], v[90:91], v[84:85], v[90:91] op_sel_hi:[0,1,0]
	v_min_u32_e32 v66, 1, v66
	v_rcp_f32_e32 v84, v84
	v_rcp_f32_e32 v85, v85
	v_or_b32_e32 v66, v67, v66
	v_pk_mul_f32 v[72:73], v[68:69], v[80:81]
	v_cvt_f32_u32_e32 v68, v184
	v_cvt_f32_u32_e32 v69, v66
	v_exp_f32_e32 v86, v86
	v_exp_f32_e32 v87, v87
	v_pk_mul_f32 v[74:75], v[74:75], v[84:85]
	s_add_u32 s8, s8, s88
	v_cvt_pk_bf16_f32 v66, v74, v75
	v_fmamk_f32 v74, v68, 0x30000000, v209
	v_ldexp_f32 v68, v69, s93
	v_pk_fma_f32 v[86:87], v[90:91], v[86:87], v[90:91] op_sel_hi:[0,1,0]
	v_fmac_f32_e32 v74, 2.0, v68
	v_rcp_f32_e32 v86, v86
	v_rcp_f32_e32 v87, v87
	v_rsq_f32_e32 v75, v74
	s_addc_u32 s9, s9, 0
	v_mov_b32_e32 v146, v187
	v_pk_mul_f32 v[76:77], v[76:77], v[86:87]
	s_nop 0
	v_cvt_pk_bf16_f32 v67, v76, v77
	v_cvt_pk_bf16_f32 v68, v70, v71
	v_cvt_pk_bf16_f32 v69, v72, v73
	global_store_dwordx4 v138, v[66:69], s[8:9]
	s_add_u32 s8, s43, s82
	s_addc_u32 s9, s90, s84
	v_mul_f32_e32 v66, 0xbfb8aa3b, v75
	v_pk_mul_f32 v[68:69], v[62:63], v[66:67] op_sel_hi:[1,0]
	v_pk_mul_f32 v[62:63], v[54:55], v[66:67] op_sel_hi:[1,0]
	v_pk_mul_f32 v[70:71], v[64:65], v[66:67] op_sel_hi:[1,0]
	v_exp_f32_e32 v62, v62
	v_exp_f32_e32 v63, v63
	v_pk_mul_f32 v[64:65], v[56:57], v[66:67] op_sel_hi:[1,0]
	v_exp_f32_e32 v68, v68
	v_exp_f32_e32 v64, v64
	v_exp_f32_e32 v65, v65
	v_pk_fma_f32 v[62:63], v[74:75], v[62:63], v[74:75] op_sel_hi:[0,1,0]
	v_rcp_f32_e32 v62, v62
	v_rcp_f32_e32 v63, v63
	v_exp_f32_e32 v69, v69
	v_pk_fma_f32 v[64:65], v[74:75], v[64:65], v[74:75] op_sel_hi:[0,1,0]
	v_rcp_f32_e32 v64, v64
	v_rcp_f32_e32 v65, v65
	v_pk_mul_f32 v[54:55], v[50:51], v[62:63]
	v_lshlrev_b64 v[50:51], s42, v[146:147]
	v_pk_fma_f32 v[68:69], v[74:75], v[68:69], v[74:75] op_sel_hi:[0,1,0]
	v_min_u32_e32 v50, 1, v50
	v_rcp_f32_e32 v68, v68
	v_rcp_f32_e32 v69, v69
	v_or_b32_e32 v50, v51, v50
	v_pk_mul_f32 v[56:57], v[52:53], v[64:65]
	v_cvt_f32_u32_e32 v52, v186
	v_cvt_f32_u32_e32 v53, v50
	v_exp_f32_e32 v70, v70
	v_exp_f32_e32 v71, v71
	v_pk_mul_f32 v[58:59], v[58:59], v[68:69]
	s_add_u32 s8, s8, s88
	v_cvt_pk_bf16_f32 v50, v58, v59
	v_fmamk_f32 v58, v52, 0x30000000, v209
	v_ldexp_f32 v52, v53, s93
	v_pk_fma_f32 v[70:71], v[74:75], v[70:71], v[74:75] op_sel_hi:[0,1,0]
	v_fmac_f32_e32 v58, 2.0, v52
	v_rcp_f32_e32 v70, v70
	v_rcp_f32_e32 v71, v71
	v_rsq_f32_e32 v59, v58
	s_addc_u32 s9, s9, 0
	v_mov_b32_e32 v146, v189
	v_pk_mul_f32 v[60:61], v[60:61], v[70:71]
	s_nop 0
	v_cvt_pk_bf16_f32 v51, v60, v61
	v_cvt_pk_bf16_f32 v52, v54, v55
	v_cvt_pk_bf16_f32 v53, v56, v57
	global_store_dwordx4 v138, v[50:53], s[8:9]
	s_add_u32 s8, s43, s85
	s_addc_u32 s9, s90, s22
	v_mul_f32_e32 v50, 0xbfb8aa3b, v59
	v_pk_mul_f32 v[52:53], v[46:47], v[50:51] op_sel_hi:[1,0]
	v_pk_mul_f32 v[46:47], v[38:39], v[50:51] op_sel_hi:[1,0]
	v_pk_mul_f32 v[54:55], v[48:49], v[50:51] op_sel_hi:[1,0]
	v_exp_f32_e32 v46, v46
	v_exp_f32_e32 v47, v47
	v_pk_mul_f32 v[48:49], v[40:41], v[50:51] op_sel_hi:[1,0]
	v_exp_f32_e32 v52, v52
	v_exp_f32_e32 v48, v48
	v_exp_f32_e32 v49, v49
	v_pk_fma_f32 v[46:47], v[58:59], v[46:47], v[58:59] op_sel_hi:[0,1,0]
	v_rcp_f32_e32 v46, v46
	v_rcp_f32_e32 v47, v47
	v_exp_f32_e32 v53, v53
	v_pk_fma_f32 v[48:49], v[58:59], v[48:49], v[58:59] op_sel_hi:[0,1,0]
	v_rcp_f32_e32 v48, v48
	v_rcp_f32_e32 v49, v49
	v_pk_mul_f32 v[38:39], v[34:35], v[46:47]
	v_lshlrev_b64 v[34:35], s42, v[146:147]
	v_pk_fma_f32 v[52:53], v[58:59], v[52:53], v[58:59] op_sel_hi:[0,1,0]
	v_min_u32_e32 v34, 1, v34
	v_rcp_f32_e32 v52, v52
	v_rcp_f32_e32 v53, v53
	v_or_b32_e32 v34, v35, v34
	v_pk_mul_f32 v[40:41], v[36:37], v[48:49]
	v_cvt_f32_u32_e32 v36, v188
	v_cvt_f32_u32_e32 v37, v34
	v_exp_f32_e32 v54, v54
	v_exp_f32_e32 v55, v55
	v_pk_mul_f32 v[42:43], v[42:43], v[52:53]
	s_add_u32 s8, s8, s88
	v_cvt_pk_bf16_f32 v34, v42, v43
	v_fmamk_f32 v42, v36, 0x30000000, v209
	v_ldexp_f32 v36, v37, s93
	v_pk_fma_f32 v[54:55], v[58:59], v[54:55], v[58:59] op_sel_hi:[0,1,0]
	v_fmac_f32_e32 v42, 2.0, v36
	v_rcp_f32_e32 v54, v54
	v_rcp_f32_e32 v55, v55
	v_rsq_f32_e32 v43, v42
	s_addc_u32 s9, s9, 0
	v_mov_b32_e32 v146, v191
	v_pk_mul_f32 v[44:45], v[44:45], v[54:55]
	s_nop 0
	v_cvt_pk_bf16_f32 v35, v44, v45
	v_cvt_pk_bf16_f32 v36, v38, v39
	v_cvt_pk_bf16_f32 v37, v40, v41
	global_store_dwordx4 v138, v[34:37], s[8:9]
	s_add_u32 s8, s43, s83
	s_addc_u32 s9, s90, s12
	v_mul_f32_e32 v34, 0xbfb8aa3b, v43
	v_pk_mul_f32 v[36:37], v[30:31], v[34:35] op_sel_hi:[1,0]
	v_pk_mul_f32 v[30:31], v[22:23], v[34:35] op_sel_hi:[1,0]
	v_pk_mul_f32 v[38:39], v[32:33], v[34:35] op_sel_hi:[1,0]
	v_exp_f32_e32 v30, v30
	v_exp_f32_e32 v31, v31
	v_pk_mul_f32 v[32:33], v[24:25], v[34:35] op_sel_hi:[1,0]
	v_exp_f32_e32 v36, v36
	v_exp_f32_e32 v32, v32
	v_exp_f32_e32 v33, v33
	v_pk_fma_f32 v[30:31], v[42:43], v[30:31], v[42:43] op_sel_hi:[0,1,0]
	v_rcp_f32_e32 v30, v30
	v_rcp_f32_e32 v31, v31
	v_exp_f32_e32 v37, v37
	v_pk_fma_f32 v[32:33], v[42:43], v[32:33], v[42:43] op_sel_hi:[0,1,0]
	v_rcp_f32_e32 v32, v32
	v_rcp_f32_e32 v33, v33
	v_pk_mul_f32 v[22:23], v[18:19], v[30:31]
	v_lshlrev_b64 v[18:19], s42, v[146:147]
	v_pk_fma_f32 v[36:37], v[42:43], v[36:37], v[42:43] op_sel_hi:[0,1,0]
	v_min_u32_e32 v18, 1, v18
	v_rcp_f32_e32 v36, v36
	v_rcp_f32_e32 v37, v37
	v_or_b32_e32 v18, v19, v18
	v_pk_mul_f32 v[24:25], v[20:21], v[32:33]
	v_cvt_f32_u32_e32 v20, v190
	v_cvt_f32_u32_e32 v21, v18
	v_exp_f32_e32 v38, v38
	v_exp_f32_e32 v39, v39
	v_pk_mul_f32 v[26:27], v[26:27], v[36:37]
	s_add_u32 s8, s8, s88
	v_cvt_pk_bf16_f32 v18, v26, v27
	v_fmamk_f32 v26, v20, 0x30000000, v209
	v_ldexp_f32 v20, v21, s93
	v_pk_fma_f32 v[38:39], v[42:43], v[38:39], v[42:43] op_sel_hi:[0,1,0]
	v_fmac_f32_e32 v26, 2.0, v20
	v_rcp_f32_e32 v38, v38
	v_rcp_f32_e32 v39, v39
	v_rsq_f32_e32 v27, v26
	s_addc_u32 s9, s9, 0
	v_pk_mul_f32 v[28:29], v[28:29], v[38:39]
	s_nop 0
	v_cvt_pk_bf16_f32 v19, v28, v29
	v_cvt_pk_bf16_f32 v20, v22, v23
	v_cvt_pk_bf16_f32 v21, v24, v25
	global_store_dwordx4 v138, v[18:21], s[8:9]
	s_add_u32 s8, s43, s86
	s_addc_u32 s9, s90, s87
	v_mul_f32_e32 v18, 0xbfb8aa3b, v27
	v_pk_mul_f32 v[20:21], v[14:15], v[18:19] op_sel_hi:[1,0]
	v_pk_mul_f32 v[22:23], v[16:17], v[18:19] op_sel_hi:[1,0]
	v_pk_mul_f32 v[14:15], v[6:7], v[18:19] op_sel_hi:[1,0]
	v_pk_mul_f32 v[16:17], v[8:9], v[18:19] op_sel_hi:[1,0]
	v_exp_f32_e32 v20, v20
	v_exp_f32_e32 v21, v21
	v_exp_f32_e32 v22, v22
	v_exp_f32_e32 v23, v23
	v_exp_f32_e32 v14, v14
	v_exp_f32_e32 v15, v15
	v_exp_f32_e32 v16, v16
	v_exp_f32_e32 v17, v17
	v_pk_fma_f32 v[20:21], v[26:27], v[20:21], v[26:27] op_sel_hi:[0,1,0]
	v_pk_fma_f32 v[22:23], v[26:27], v[22:23], v[26:27] op_sel_hi:[0,1,0]
	v_pk_fma_f32 v[14:15], v[26:27], v[14:15], v[26:27] op_sel_hi:[0,1,0]
	v_pk_fma_f32 v[16:17], v[26:27], v[16:17], v[26:27] op_sel_hi:[0,1,0]
	v_rcp_f32_e32 v20, v20
	v_rcp_f32_e32 v21, v21
	v_rcp_f32_e32 v22, v22
	v_rcp_f32_e32 v23, v23
	v_rcp_f32_e32 v14, v14
	v_rcp_f32_e32 v15, v15
	v_rcp_f32_e32 v16, v16
	v_rcp_f32_e32 v17, v17
	s_add_u32 s8, s8, s88
	s_addc_u32 s9, s9, 0
	v_pk_mul_f32 v[10:11], v[10:11], v[20:21]
	v_pk_mul_f32 v[12:13], v[12:13], v[22:23]
	v_pk_mul_f32 v[6:7], v[2:3], v[14:15]
	v_pk_mul_f32 v[8:9], v[4:5], v[16:17]
	v_cvt_pk_bf16_f32 v2, v10, v11
	v_cvt_pk_bf16_f32 v3, v12, v13
	v_cvt_pk_bf16_f32 v4, v6, v7
	s_andn2_b64 vcc, exec, s[48:49]
	v_cvt_pk_bf16_f32 v5, v8, v9
	global_store_dwordx4 v138, v[2:5], s[8:9]
	s_mov_b64 s[8:9], -1
	s_cbranch_vccnz .LBB0_1869
	s_andn2_b64 vcc, exec, s[44:45]
	s_cbranch_vccnz .LBB0_1868
	s_barrier
	s_branch .LBB0_1868
